# in-proj: remap N-tiles of the second M-group so every workgroup gets exactly one V-transposed-store unit
# baseline (speedup 1.0000x reference)
;     __device__ bool next(int i, Unit& u) const {
;         const long L = (long)i * G + c; if (L >= nwg) return false;
;         int wgid = (int)L; { const int q = nwg / NXCD, r = nwg % NXCD, xcd = wgid % NXCD, off = wgid / NXCD; wgid = (xcd < r ? xcd * (q + 1) : r * (q + 1) + (xcd - r) * q) + off; }
;         const int nig = WGM * nN, gid = wgid / nig, fm = gid * WGM, gsz = (nM - fm) < WGM ? (nM - fm) : WGM;
;         u.pm = fm + ((wgid % nig) % gsz); u.pn = (wgid % nig) / gsz; u.bz = 0;
;         u.a_off = (unsigned)(u.pm * BM) * (unsigned)lda; u.b_off = (unsigned)(u.pn * BM) * (unsigned)ldb; return true;
.LBB0_688:
	s_ashr_i32 s5, s5, 3
	s_add_i32 s5, s11, s5
	s_ashr_i32 s8, s5, 31
	s_lshr_b32 s8, s8, 26
	s_add_i32 s8, s5, s8
	s_ashr_i32 s9, s8, 6
	s_and_b32 s8, s8, 0xffc0
	s_sub_i32 s5, s5, s8
	s_bfe_i32 s8, s5, 0x80000
	s_bfe_u32 s8, s8, 0x3000c
	s_add_i32 s8, s5, s8
	s_bfe_i32 s10, s8, 0x80000
	s_and_b32 s8, s8, 0xf8
	s_sub_i32 s5, s5, s8
	s_lshl_b32 s9, s9, 3
	s_sext_i32_i8 s5, s5
	s_sext_i32_i16 s10, s10
	s_add_i32 s94, s9, s5
	s_ashr_i32 s79, s10, 3
	s_lshr_b32 s8, s9, 2
	s_and_b32 s8, s8, 2
	s_xor_b32 s79, s79, s8
	s_lshl_b32 s18, s94, 18
	s_lshl_b32 s56, s79, 18
	s_mov_b32 s57, s19
	s_mov_b64 s[54:55], s[18:19]

;     __device__ bool next(int i, Unit& u) const {
;         const long L = (long)i * G + c; if (L >= nwg) return false;
;         int wgid = (int)L; { const int q = nwg / NXCD, r = nwg % NXCD, xcd = wgid % NXCD, off = wgid / NXCD; wgid = (xcd < r ? xcd * (q + 1) : r * (q + 1) + (xcd - r) * q) + off; }
;         const int nig = WGM * nN, gid = wgid / nig, fm = gid * WGM, gsz = (nM - fm) < WGM ? (nM - fm) : WGM;
;         u.pm = fm + ((wgid % nig) % gsz); u.pn = (wgid % nig) / gsz; u.bz = 0;
;         u.a_off = (unsigned)(u.pm * BM) * (unsigned)lda; u.b_off = (unsigned)(u.pn * BM) * (unsigned)ldb; return true;
.LBB0_747:
	s_ashr_i32 s12, s14, 3
	s_add_i32 s12, s18, s12
	s_ashr_i32 s13, s12, 31
	s_lshr_b32 s13, s13, 26
	s_add_i32 s13, s12, s13
	s_ashr_i32 s14, s13, 6
	s_lshl_b32 s14, s14, 3
	s_sub_i32 s15, 0x80, s14
	s_min_i32 s15, s15, 8
	s_abs_i32 s18, s15
	v_cvt_f32_u32_e32 v131, s18
	s_sub_i32 s31, 0, s18
	s_andn2_b32 s13, s13, 63
	s_sub_i32 s12, s12, s13
	v_rcp_iflag_f32_e32 v131, v131
	s_abs_i32 s13, s12
	s_xor_b32 s25, s12, s15
	s_ashr_i32 s25, s25, 31
	v_mul_f32_e32 v131, 0x4f7ffffe, v131
	v_cvt_u32_f32_e32 v131, v131
	s_nop 0
	v_readfirstlane_b32 s33, v131
	s_mul_i32 s31, s31, s33
	s_mul_hi_u32 s31, s33, s31
	s_add_i32 s33, s33, s31
	s_mul_hi_u32 s31, s13, s33
	s_mul_i32 s33, s31, s18
	s_sub_i32 s13, s13, s33
	s_add_i32 s39, s31, 1
	s_sub_i32 s33, s13, s18
	s_cmp_ge_u32 s13, s18
	s_cselect_b32 s31, s39, s31
	s_cselect_b32 s13, s33, s13
	s_add_i32 s33, s31, 1
	s_cmp_ge_u32 s13, s18
	s_cselect_b32 s13, s33, s31
	s_xor_b32 s13, s13, s25
	s_sub_i32 s88, s13, s25
	s_mul_i32 s13, s88, s15
	s_sub_i32 s12, s12, s13
	s_add_i32 s78, s14, s12
	s_lshl_b32 s18, s78, 18
	s_lshr_b32 s13, s14, 2
	s_and_b32 s13, s13, 2
	s_xor_b32 s88, s88, s13
	s_lshl_b32 s64, s88, 18
